# attention: batched LDS reads with counted waits, sink via scalar load, output stores left in flight across items
# speedup vs baseline: 1.0060x; 1.0060x over previous
.Lmy_att_top2:
	v_mov_b64_e32 v[76:77], v[126:127]
	v_mov_b64_e32 v[72:73], v[122:123]
	v_mov_b64_e32 v[68:69], v[118:119]
	v_mov_b64_e32 v[64:65], v[114:115]
	s_xor_b32 s14, s14, 1
	s_add_i32 s10, s10, s24
	s_add_i32 s15, s15, s53
	s_add_i32 s1, s1, s61
	s_andn2_b64 vcc, exec, s[38:39]
	v_mov_b64_e32 v[78:79], v[128:129]
	v_mov_b64_e32 v[74:75], v[124:125]
	v_mov_b64_e32 v[70:71], v[120:121]
	v_mov_b64_e32 v[66:67], v[116:117]
	s_cbranch_vccz .LBB0_1409
	s_and_b32 s4, s1, 12
	s_cmpk_gt_i32 s33, 0x7ff
	s_mov_b64 s[2:3], -1
	s_waitcnt lgkmcnt(0)
	s_barrier
	s_branch .Lmy_att_body
.LBB0_1319:
	v_add_u32_e32 v96, s46, v176
	s_lshl_b32 s2, s0, 6
	s_ashr_i32 s3, s2, 31
	v_ashrrev_i32_e32 v97, 31, v96
	v_lshl_add_u64 v[98:99], s[2:3], 1, v[170:171]
	v_lshlrev_b64 v[100:101], 11, v[96:97]
	v_lshl_add_u64 v[100:101], v[98:99], 0, v[100:101]
	v_cvt_pk_bf16_f32 v64, v64, v113
	s_nop 0
	global_store_short v[100:101], v64, off
	v_cvt_pk_bf16_f32 v64, v80, v113
	global_store_short v[100:101], v64, off offset:64
	v_add_u32_e32 v100, 1, v96
	v_ashrrev_i32_e32 v101, 31, v100
	v_lshlrev_b64 v[100:101], 11, v[100:101]
	v_lshl_add_u64 v[100:101], v[98:99], 0, v[100:101]
	v_cvt_pk_bf16_f32 v64, v65, v113
	global_store_short v[100:101], v64, off
	v_cvt_pk_bf16_f32 v64, v81, v113
	global_store_short v[100:101], v64, off offset:64
	v_add_u32_e32 v64, 2, v96
	v_ashrrev_i32_e32 v65, 31, v64
	v_lshlrev_b64 v[64:65], 11, v[64:65]
	v_lshl_add_u64 v[64:65], v[98:99], 0, v[64:65]
	v_cvt_pk_bf16_f32 v66, v66, v113
	global_store_short v[64:65], v66, off
	v_cvt_pk_bf16_f32 v66, v82, v113
	global_store_short v[64:65], v66, off offset:64
	v_add_u32_e32 v64, 3, v96
	v_ashrrev_i32_e32 v65, 31, v64
	v_lshlrev_b64 v[64:65], 11, v[64:65]
	v_lshl_add_u64 v[64:65], v[98:99], 0, v[64:65]
	v_cvt_pk_bf16_f32 v66, v67, v113
	global_store_short v[64:65], v66, off
	v_cvt_pk_bf16_f32 v66, v83, v113
	global_store_short v[64:65], v66, off offset:64
	v_add_u32_e32 v64, 8, v96
	v_ashrrev_i32_e32 v65, 31, v64
	v_lshlrev_b64 v[64:65], 11, v[64:65]
	v_lshl_add_u64 v[64:65], v[98:99], 0, v[64:65]
	v_cvt_pk_bf16_f32 v66, v68, v113
	global_store_short v[64:65], v66, off
	v_cvt_pk_bf16_f32 v66, v84, v113
	global_store_short v[64:65], v66, off offset:64
	v_add_u32_e32 v64, 9, v96
	v_ashrrev_i32_e32 v65, 31, v64
	v_lshlrev_b64 v[64:65], 11, v[64:65]
	v_lshl_add_u64 v[64:65], v[98:99], 0, v[64:65]
	v_cvt_pk_bf16_f32 v66, v69, v113
	global_store_short v[64:65], v66, off
	v_cvt_pk_bf16_f32 v66, v85, v113
	global_store_short v[64:65], v66, off offset:64
	v_add_u32_e32 v64, 10, v96
	v_ashrrev_i32_e32 v65, 31, v64
	v_lshlrev_b64 v[64:65], 11, v[64:65]
	v_lshl_add_u64 v[64:65], v[98:99], 0, v[64:65]
	v_cvt_pk_bf16_f32 v66, v70, v113
	global_store_short v[64:65], v66, off
	v_cvt_pk_bf16_f32 v66, v86, v113
	global_store_short v[64:65], v66, off offset:64
	v_add_u32_e32 v64, 11, v96
	v_ashrrev_i32_e32 v65, 31, v64
	v_lshlrev_b64 v[64:65], 11, v[64:65]
	v_lshl_add_u64 v[64:65], v[98:99], 0, v[64:65]
	v_cvt_pk_bf16_f32 v66, v71, v113
	global_store_short v[64:65], v66, off
	v_cvt_pk_bf16_f32 v66, v87, v113
	global_store_short v[64:65], v66, off offset:64
	v_add_u32_e32 v64, 16, v96
	v_ashrrev_i32_e32 v65, 31, v64
	v_lshlrev_b64 v[64:65], 11, v[64:65]
	v_lshl_add_u64 v[64:65], v[98:99], 0, v[64:65]
	v_cvt_pk_bf16_f32 v66, v72, v113
	global_store_short v[64:65], v66, off
	v_cvt_pk_bf16_f32 v66, v88, v113
	global_store_short v[64:65], v66, off offset:64
	v_add_u32_e32 v64, 17, v96
	v_ashrrev_i32_e32 v65, 31, v64
	v_lshlrev_b64 v[64:65], 11, v[64:65]
	v_lshl_add_u64 v[64:65], v[98:99], 0, v[64:65]
	v_cvt_pk_bf16_f32 v66, v73, v113
	global_store_short v[64:65], v66, off
	v_cvt_pk_bf16_f32 v66, v89, v113
	global_store_short v[64:65], v66, off offset:64
	v_add_u32_e32 v64, 18, v96
	v_ashrrev_i32_e32 v65, 31, v64
	v_lshlrev_b64 v[64:65], 11, v[64:65]
	v_lshl_add_u64 v[64:65], v[98:99], 0, v[64:65]
	v_cvt_pk_bf16_f32 v66, v74, v113
	global_store_short v[64:65], v66, off
	v_cvt_pk_bf16_f32 v66, v90, v113
	global_store_short v[64:65], v66, off offset:64
	v_add_u32_e32 v64, 19, v96
	v_ashrrev_i32_e32 v65, 31, v64
	v_lshlrev_b64 v[64:65], 11, v[64:65]
	v_lshl_add_u64 v[64:65], v[98:99], 0, v[64:65]
	v_cvt_pk_bf16_f32 v66, v75, v113
	global_store_short v[64:65], v66, off
	v_cvt_pk_bf16_f32 v66, v91, v113
	global_store_short v[64:65], v66, off offset:64
	v_add_u32_e32 v64, 24, v96
	v_ashrrev_i32_e32 v65, 31, v64
	v_lshlrev_b64 v[64:65], 11, v[64:65]
	v_lshl_add_u64 v[64:65], v[98:99], 0, v[64:65]
	v_cvt_pk_bf16_f32 v66, v76, v113
	global_store_short v[64:65], v66, off
	v_cvt_pk_bf16_f32 v66, v92, v113
	global_store_short v[64:65], v66, off offset:64
	v_add_u32_e32 v64, 25, v96
	v_ashrrev_i32_e32 v65, 31, v64
	v_lshlrev_b64 v[64:65], 11, v[64:65]
	v_lshl_add_u64 v[64:65], v[98:99], 0, v[64:65]
	v_cvt_pk_bf16_f32 v66, v77, v113
	global_store_short v[64:65], v66, off
	v_cvt_pk_bf16_f32 v66, v93, v113
	global_store_short v[64:65], v66, off offset:64
	v_add_u32_e32 v64, 26, v96
	v_ashrrev_i32_e32 v65, 31, v64
	v_lshlrev_b64 v[64:65], 11, v[64:65]
	v_lshl_add_u64 v[64:65], v[98:99], 0, v[64:65]
	v_cvt_pk_bf16_f32 v66, v78, v113
	global_store_short v[64:65], v66, off
	v_cvt_pk_bf16_f32 v66, v94, v113
	global_store_short v[64:65], v66, off offset:64
	v_add_u32_e32 v64, 27, v96
	v_ashrrev_i32_e32 v65, 31, v64
	v_lshlrev_b64 v[64:65], 11, v[64:65]
	v_lshl_add_u64 v[64:65], v[98:99], 0, v[64:65]
	v_cvt_pk_bf16_f32 v66, v79, v113
	global_store_short v[64:65], v66, off
	v_cvt_pk_bf16_f32 v66, v95, v113
	global_store_short v[64:65], v66, off offset:64
	s_waitcnt vmcnt(32)
	s_branch .Lmy_att_top2

.Lmy_att_body:
	s_cbranch_scc0 .LBB0_1323
	v_readlane_b32 s0, v252, 28
	s_and_b32 s2, s10, 0x7fffffe0
	s_or_b32 s0, s4, s0
	s_add_i32 s62, s2, 0x4000
	s_mov_b64 s[2:3], 0

.LBB0_1376:
	s_andn2_b64 vcc, exec, s[4:5]
	s_cbranch_vccnz .LBB0_1320
	v_lshlrev_b32_e32 v80, 16, v76
	v_and_b32_e32 v76, 0xffff0000, v76
	v_lshlrev_b32_e32 v84, 16, v72
	v_and_b32_e32 v85, 0xffff0000, v72
	v_mul_f32_e32 v72, v76, v76
	v_lshlrev_b32_e32 v81, 16, v77
	v_fmac_f32_e32 v72, v80, v80
	v_and_b32_e32 v77, 0xffff0000, v77
	v_fmac_f32_e32 v72, v81, v81
	v_lshlrev_b32_e32 v82, 16, v78
	v_fmac_f32_e32 v72, v77, v77
	v_and_b32_e32 v78, 0xffff0000, v78
	v_fmac_f32_e32 v72, v82, v82
	v_lshlrev_b32_e32 v83, 16, v79
	v_fmac_f32_e32 v72, v78, v78
	v_and_b32_e32 v79, 0xffff0000, v79
	v_fmac_f32_e32 v72, v83, v83
	v_fmac_f32_e32 v72, v79, v79
	v_fmac_f32_e32 v72, v84, v84
	v_lshlrev_b32_e32 v86, 16, v73
	v_fmac_f32_e32 v72, v85, v85
	v_and_b32_e32 v87, 0xffff0000, v73
	v_fmac_f32_e32 v72, v86, v86
	v_lshlrev_b32_e32 v88, 16, v74
	v_fmac_f32_e32 v72, v87, v87
	v_and_b32_e32 v89, 0xffff0000, v74
	v_fmac_f32_e32 v72, v88, v88
	v_lshlrev_b32_e32 v90, 16, v75
	v_fmac_f32_e32 v72, v89, v89
	v_and_b32_e32 v91, 0xffff0000, v75
	v_fmac_f32_e32 v72, v90, v90
	v_lshlrev_b32_e32 v92, 16, v68
	v_fmac_f32_e32 v72, v91, v91
	v_and_b32_e32 v93, 0xffff0000, v68
	v_fmac_f32_e32 v72, v92, v92
	v_lshlrev_b32_e32 v94, 16, v69
	v_fmac_f32_e32 v72, v93, v93
	v_and_b32_e32 v95, 0xffff0000, v69
	v_fmac_f32_e32 v72, v94, v94
	v_lshlrev_b32_e32 v96, 16, v70
	v_fmac_f32_e32 v72, v95, v95
	v_and_b32_e32 v97, 0xffff0000, v70
	v_fmac_f32_e32 v72, v96, v96
	v_and_b32_e32 v68, 0xffff0000, v71
	v_lshlrev_b32_e32 v69, 16, v71
	v_fmac_f32_e32 v72, v97, v97
	v_pk_mul_f32 v[70:71], v[68:69], v[68:69]
	s_mov_b32 s2, 0x800000
	v_add_f32_e32 v71, v71, v72
	v_add_f32_e32 v74, v70, v71
	v_and_b32_e32 v70, 0xffff0000, v64
	v_lshlrev_b32_e32 v71, 16, v64
	v_pk_mul_f32 v[72:73], v[70:71], v[70:71]
	s_cmp_gt_u32 s55, 2
	v_add_f32_e32 v64, v73, v74
	v_add_f32_e32 v74, v72, v64
	v_and_b32_e32 v64, 0xffff0000, v65
	v_lshlrev_b32_e32 v65, 16, v65
	v_pk_mul_f32 v[72:73], v[64:65], v[64:65]
	s_cselect_b64 s[4:5], -1, 0
	v_add_f32_e32 v73, v73, v74
	v_add_f32_e32 v98, v72, v73
	v_and_b32_e32 v72, 0xffff0000, v66
	v_lshlrev_b32_e32 v73, 16, v66
	v_pk_mul_f32 v[74:75], v[72:73], v[72:73]
	s_cmp_lt_u32 s55, 3
	v_add_f32_e32 v66, v75, v98
	v_add_f32_e32 v98, v74, v66
	v_and_b32_e32 v66, 0xffff0000, v67
	v_lshlrev_b32_e32 v67, 16, v67
	v_pk_mul_f32 v[74:75], v[66:67], v[66:67]
	s_nop 0
	v_add_f32_e32 v75, v75, v98
	v_add_f32_e32 v74, v74, v75
	ds_bpermute_b32 v75, v175, v74
	s_waitcnt lgkmcnt(0)
	v_add_f32_e32 v74, v74, v75
	v_fmamk_f32 v74, v74, 0x3c800000, v181
	v_mul_f32_e32 v75, 0x4b800000, v74
	v_cmp_gt_f32_e32 vcc, s2, v74
	s_mul_i32 s2, s14, 0xe000
	v_add_u32_e32 v197, s2, v174
	v_cndmask_b32_e32 v74, v74, v75, vcc
	v_rsq_f32_e32 v98, v74
	ds_read_b64 v[206:207], v196 offset:16384
	ds_read_b64 v[208:209], v196 offset:16392
	ds_read_b64 v[210:211], v196 offset:16400
	ds_read_b64 v[212:213], v196 offset:16408
	ds_read_b64 v[214:215], v196 offset:16448
	ds_read_b64 v[216:217], v196 offset:16456
	ds_read_b64 v[218:219], v196 offset:16464
	ds_read_b64 v[220:221], v196 offset:16472
	v_mul_f32_e32 v99, 0x45800000, v98
	v_cndmask_b32_e32 v98, v98, v99, vcc
	v_mul_f32_e32 v80, v98, v80
	v_mul_f32_e32 v76, v98, v76
	s_waitcnt lgkmcnt(8)
	s_waitcnt lgkmcnt(7)
	v_mul_f32_e32 v74, v206, v80
	v_mul_f32_e32 v75, v207, v76
	v_cvt_pk_bf16_f32 v130, v74, v75
	v_mul_f32_e32 v76, v98, v81
	v_mul_f32_e32 v69, v98, v69
	v_mul_f32_e32 v68, v98, v68
	v_mul_f32_e32 v71, v98, v71
	s_waitcnt lgkmcnt(6)
	v_mul_f32_e32 v74, v208, v76
	v_mul_f32_e32 v76, v98, v77
	v_mul_f32_e32 v75, v209, v76
	v_cvt_pk_bf16_f32 v131, v74, v75
	v_mul_f32_e32 v76, v98, v82
	v_mul_f32_e32 v70, v98, v70
	v_mul_f32_e32 v65, v98, v65
	v_mul_f32_e32 v64, v98, v64
	s_waitcnt lgkmcnt(5)
	v_mul_f32_e32 v74, v210, v76
	v_mul_f32_e32 v76, v98, v78
	v_mul_f32_e32 v75, v211, v76
	v_cvt_pk_bf16_f32 v132, v74, v75
	v_mul_f32_e32 v76, v98, v83
	v_mul_f32_e32 v67, v98, v67
	v_mul_f32_e32 v66, v98, v66
	s_waitcnt lgkmcnt(4)
	v_mul_f32_e32 v74, v76, v212
	v_mul_f32_e32 v76, v98, v79
	v_mul_f32_e32 v75, v76, v213
	v_cvt_pk_bf16_f32 v133, v74, v75
	v_mul_f32_e32 v76, v98, v84
	s_waitcnt lgkmcnt(3)
	v_mul_f32_e32 v74, v76, v214
	v_mul_f32_e32 v76, v98, v85
	v_mul_f32_e32 v75, v76, v215
	v_cvt_pk_bf16_f32 v134, v74, v75
	v_mul_f32_e32 v76, v98, v86
	s_waitcnt lgkmcnt(2)
	v_mul_f32_e32 v74, v76, v216
	v_mul_f32_e32 v76, v98, v87
	v_mul_f32_e32 v75, v76, v217
	v_cvt_pk_bf16_f32 v135, v74, v75
	v_mul_f32_e32 v76, v98, v88
	s_waitcnt lgkmcnt(1)
	v_mul_f32_e32 v74, v76, v218
	v_mul_f32_e32 v76, v98, v89
	v_mul_f32_e32 v75, v76, v219
	v_cvt_pk_bf16_f32 v136, v74, v75
	v_mul_f32_e32 v76, v98, v90
	s_waitcnt lgkmcnt(0)
	v_mul_f32_e32 v74, v76, v220
	v_mul_f32_e32 v76, v98, v91
	v_mul_f32_e32 v75, v76, v221
	v_cvt_pk_bf16_f32 v137, v74, v75
	ds_read_b64 v[206:207], v196 offset:16512
	ds_read_b64 v[208:209], v196 offset:16520
	ds_read_b64 v[210:211], v196 offset:16528
	ds_read_b64 v[212:213], v196 offset:16536
	ds_read_b64 v[214:215], v196 offset:16576
	ds_read_b64 v[216:217], v196 offset:16584
	ds_read_b64 v[218:219], v196 offset:16592
	ds_read_b64 v[220:221], v196 offset:16600
	v_mul_f32_e32 v76, v98, v92
	s_waitcnt lgkmcnt(8)
	s_waitcnt lgkmcnt(7)
	v_mul_f32_e32 v74, v76, v206
	v_mul_f32_e32 v76, v98, v93
	v_mul_f32_e32 v75, v76, v207
	v_cvt_pk_bf16_f32 v138, v74, v75
	v_mul_f32_e32 v76, v98, v94
	s_waitcnt lgkmcnt(6)
	v_mul_f32_e32 v74, v76, v208
	v_mul_f32_e32 v76, v98, v95
	v_mul_f32_e32 v75, v76, v209
	v_cvt_pk_bf16_f32 v139, v74, v75
	v_mul_f32_e32 v76, v98, v96
	s_waitcnt lgkmcnt(5)
	v_mul_f32_e32 v74, v76, v210
	v_mul_f32_e32 v76, v98, v97
	v_mul_f32_e32 v75, v76, v211
	v_cvt_pk_bf16_f32 v140, v74, v75
	s_waitcnt lgkmcnt(4)
	v_mul_f32_e32 v69, v69, v212
	v_mul_f32_e32 v68, v68, v213
	v_cvt_pk_bf16_f32 v141, v69, v68
	s_waitcnt lgkmcnt(3)
	v_mul_f32_e32 v68, v71, v214
	v_mul_f32_e32 v69, v70, v215
	v_cvt_pk_bf16_f32 v142, v68, v69
	s_waitcnt lgkmcnt(2)
	v_mul_f32_e32 v65, v65, v216
	v_mul_f32_e32 v64, v64, v217
	v_cvt_pk_bf16_f32 v143, v65, v64
	v_mul_f32_e32 v68, v98, v73
	s_waitcnt lgkmcnt(1)
	v_mul_f32_e32 v64, v68, v218
	v_mul_f32_e32 v68, v98, v72
	v_mul_f32_e32 v65, v68, v219
	v_cvt_pk_bf16_f32 v144, v64, v65
	s_waitcnt lgkmcnt(0)
	v_mul_f32_e32 v64, v67, v220
	v_mul_f32_e32 v65, v66, v221
	v_cvt_pk_bf16_f32 v145, v64, v65
	ds_read_b128 v[206:209], v197 offset:16896
	ds_read_b128 v[218:221], v197 offset:17920
	ds_read_b128 v[222:225], v197 offset:18944
	ds_read_b128 v[226:229], v197 offset:19968
	ds_read_b128 v[230:233], v197 offset:20992
	ds_read_b128 v[234:237], v197 offset:26112
	ds_read_b128 v[238:241], v197 offset:22016
	ds_read_b128 v[242:245], v197 offset:23040
	s_waitcnt lgkmcnt(8)
	s_waitcnt lgkmcnt(7)
	v_mfma_f32_32x32x16_bf16 v[96:111], v[206:209], v[130:133], 0
	s_waitcnt lgkmcnt(6)
	v_mfma_f32_32x32x16_bf16 v[96:111], v[218:221], v[134:137], v[96:111]
	s_waitcnt lgkmcnt(5)
	v_mfma_f32_32x32x16_bf16 v[96:111], v[222:225], v[138:141], v[96:111]
	s_waitcnt lgkmcnt(4)
	v_mfma_f32_32x32x16_bf16 v[96:111], v[226:229], v[142:145], v[96:111]
	s_nop 10
	s_waitcnt lgkmcnt(3)
	v_mfma_f32_32x32x16_bf16 v[80:95], v[230:233], v[130:133], 0
	s_waitcnt lgkmcnt(1)
	v_mfma_f32_32x32x16_bf16 v[80:95], v[238:241], v[134:137], v[80:95]
	s_waitcnt lgkmcnt(0)
	v_mfma_f32_32x32x16_bf16 v[80:95], v[242:245], v[138:141], v[80:95]
	ds_read_b128 v[206:209], v197 offset:24064
	ds_read_b128 v[218:221], v197 offset:25088
	ds_read_b128 v[222:225], v197 offset:27136
	ds_read_b128 v[226:229], v197 offset:28160
	s_waitcnt lgkmcnt(4)
	s_waitcnt lgkmcnt(3)
	v_mfma_f32_32x32x16_bf16 v[80:95], v[206:209], v[142:145], v[80:95]
	s_waitcnt lgkmcnt(2)
	v_mfma_f32_32x32x16_bf16 v[64:79], v[218:221], v[130:133], 0
	v_mfma_f32_32x32x16_bf16 v[64:79], v[234:237], v[134:137], v[64:79]
	s_waitcnt lgkmcnt(1)
	v_mfma_f32_32x32x16_bf16 v[64:79], v[222:225], v[138:141], v[64:79]
	s_waitcnt lgkmcnt(0)
	v_mfma_f32_32x32x16_bf16 v[64:79], v[226:229], v[142:145], v[64:79]
	s_cbranch_scc1 .LBB0_1379
	ds_read_b128 v[206:209], v197 offset:29184
	ds_read_b128 v[210:213], v197 offset:30208
	ds_read_b128 v[214:217], v197 offset:31232
	ds_read_b128 v[218:221], v197 offset:32256
	s_waitcnt lgkmcnt(4)
	s_waitcnt lgkmcnt(3)
	v_mfma_f32_32x32x16_bf16 v[48:63], v[206:209], v[130:133], 0
	s_waitcnt lgkmcnt(2)
	v_mfma_f32_32x32x16_bf16 v[48:63], v[210:213], v[134:137], v[48:63]
	s_waitcnt lgkmcnt(1)
	v_mfma_f32_32x32x16_bf16 v[48:63], v[214:217], v[138:141], v[48:63]
	s_waitcnt lgkmcnt(0)
	v_mfma_f32_32x32x16_bf16 v[48:63], v[218:221], v[142:145], v[48:63]
.LBB0_1379:
	s_cmp_gt_u32 s55, 3
	s_cselect_b64 s[6:7], -1, 0
	s_cmp_lt_u32 s55, 4
	s_cbranch_scc1 .LBB0_1381
	ds_read_b128 v[206:209], v197 offset:33280
	ds_read_b128 v[210:213], v197 offset:34304
	ds_read_b128 v[214:217], v197 offset:35328
	ds_read_b128 v[218:221], v197 offset:36352
	s_waitcnt lgkmcnt(4)
	s_waitcnt lgkmcnt(3)
	v_mfma_f32_32x32x16_bf16 v[32:47], v[206:209], v[130:133], 0
	s_waitcnt lgkmcnt(2)
	v_mfma_f32_32x32x16_bf16 v[32:47], v[210:213], v[134:137], v[32:47]
	s_waitcnt lgkmcnt(1)
	v_mfma_f32_32x32x16_bf16 v[32:47], v[214:217], v[138:141], v[32:47]
	s_waitcnt lgkmcnt(0)
	v_mfma_f32_32x32x16_bf16 v[32:47], v[218:221], v[142:145], v[32:47]
.LBB0_1381:
	s_cmp_gt_u32 s55, 4
	s_mov_b32 s46, s62
	s_mov_b32 s25, s61
	s_cselect_b64 s[8:9], -1, 0
	s_cmp_lt_u32 s55, 5
	s_cbranch_scc1 .LBB0_1383
	ds_read_b128 v[206:209], v197 offset:37376
	ds_read_b128 v[210:213], v197 offset:38400
	ds_read_b128 v[214:217], v197 offset:39424
	ds_read_b128 v[218:221], v197 offset:40448
	s_waitcnt lgkmcnt(4)
	s_waitcnt lgkmcnt(3)
	v_mfma_f32_32x32x16_bf16 v[16:31], v[206:209], v[130:133], 0
	s_waitcnt lgkmcnt(2)
	v_mfma_f32_32x32x16_bf16 v[16:31], v[210:213], v[134:137], v[16:31]
	s_waitcnt lgkmcnt(1)
	v_mfma_f32_32x32x16_bf16 v[16:31], v[214:217], v[138:141], v[16:31]
	s_waitcnt lgkmcnt(0)
	v_mfma_f32_32x32x16_bf16 v[16:31], v[218:221], v[142:145], v[16:31]
.LBB0_1383:
	s_cmp_gt_u32 s55, 5
	s_mov_b64 s[12:13], s[58:59]
	s_cselect_b64 s[96:97], -1, 0
	s_cmp_lt_u32 s55, 6
	s_cbranch_scc1 .LBB0_1385
	ds_read_b128 v[206:209], v197 offset:41472
	ds_read_b128 v[210:213], v197 offset:42496
	ds_read_b128 v[214:217], v197 offset:43520
	ds_read_b128 v[218:221], v197 offset:44544
	s_waitcnt lgkmcnt(4)
	s_waitcnt lgkmcnt(3)
	v_mfma_f32_32x32x16_bf16 v[0:15], v[206:209], v[130:133], 0
	s_waitcnt lgkmcnt(2)
	v_mfma_f32_32x32x16_bf16 v[0:15], v[210:213], v[134:137], v[0:15]
	s_waitcnt lgkmcnt(1)
	v_mfma_f32_32x32x16_bf16 v[0:15], v[214:217], v[138:141], v[0:15]
	s_waitcnt lgkmcnt(0)
	v_mfma_f32_32x32x16_bf16 v[0:15], v[218:221], v[142:145], v[0:15]
.LBB0_1385:
	v_readlane_b32 s2, v252, 48
	s_add_i32 s2, s0, s2
	s_ashr_i32 s3, s2, 31
	v_readlane_b32 s56, v253, 0
	s_lshl_b64 s[2:3], s[2:3], 2
	v_readlane_b32 s58, v253, 2
	v_readlane_b32 s59, v253, 3
	s_add_u32 s2, s58, s2
	s_addc_u32 s3, s59, s3
	s_load_dword s32, s[2:3], 0x0
	v_or_b32_e32 v105, s54, v172
	v_add_u32_e32 v107, s30, v172
	s_lshl_b32 s2, s0, 10
	v_sub_u32_e32 v106, s31, v105
	v_sub_u32_e32 v206, v176, v107
	v_max_i32_e32 v206, 0xffffff51, v206
	v_lshl_add_u32 v206, v206, 2, s2
	ds_read_b32 v210, v206 offset:700
	v_sub_u32_e32 v207, v177, v107
	v_max_i32_e32 v207, 0xffffff51, v207
	v_lshl_add_u32 v207, v207, 2, s2
	ds_read_b32 v211, v207 offset:700
	v_sub_u32_e32 v208, v178, v107
	v_max_i32_e32 v208, 0xffffff51, v208
	v_lshl_add_u32 v208, v208, 2, s2
	ds_read_b32 v212, v208 offset:700
	s_add_i32 s2, s2, 0
	s_mov_b32 s3, 0xf149f2ca
	s_andn2_b64 vcc, exec, s[4:5]
	v_readlane_b32 s57, v253, 1
	s_waitcnt lgkmcnt(3)
	s_waitcnt lgkmcnt(2)
	v_add_f32_e32 v96, v96, v210
	s_waitcnt lgkmcnt(1)
	v_add_f32_e32 v97, v97, v211
	v_readlane_b32 s60, v253, 4
	v_readlane_b32 s61, v253, 5
	v_readlane_b32 s62, v253, 6
	v_readlane_b32 s63, v253, 7
	s_waitcnt lgkmcnt(0)
	v_add_f32_e32 v98, v98, v212
	s_waitcnt vmcnt(63) lgkmcnt(0)
	v_mov_b32_e32 v104, s32
	v_mul_f32_e32 v104, 0x3fb8aa3b, v104
	v_max_f32_e32 v105, v104, v96
	v_max3_f32 v108, v105, v97, v98
	v_sub_u32_e32 v206, v179, v107
	v_max_i32_e32 v206, 0xffffff51, v206
	v_lshl_add_u32 v206, v206, 2, s2
	ds_read_b32 v210, v206 offset:700
	v_sub_u32_e32 v207, v192, v107
	v_max_i32_e32 v207, 0xffffff51, v207
	v_lshl_add_u32 v207, v207, 2, s2
	ds_read_b32 v211, v207 offset:700
	v_sub_u32_e32 v208, v193, v107
	v_max_i32_e32 v208, 0xffffff51, v208
	v_lshl_add_u32 v208, v208, 2, s2
	ds_read_b32 v212, v208 offset:700
	v_sub_u32_e32 v209, v194, v107
	v_max_i32_e32 v209, 0xffffff51, v209
	v_lshl_add_u32 v209, v209, 2, s2
	ds_read_b32 v213, v209 offset:700
	v_sub_u32_e32 v206, v195, v107
	v_max_i32_e32 v206, 0xffffff51, v206
	v_lshl_add_u32 v206, v206, 2, s2
	ds_read_b32 v214, v206 offset:700
	s_waitcnt lgkmcnt(5)
	s_waitcnt lgkmcnt(4)
	v_add_f32_e32 v105, v99, v210
	s_waitcnt lgkmcnt(3)
	v_add_f32_e32 v99, v100, v211
	v_max3_f32 v108, v108, v105, v99
	s_waitcnt lgkmcnt(2)
	v_add_f32_e32 v100, v101, v212
	s_waitcnt lgkmcnt(1)
	v_add_f32_e32 v101, v102, v213
	v_max3_f32 v108, v108, v100, v101
	s_waitcnt lgkmcnt(0)
	v_add_f32_e32 v102, v103, v214
	v_lshlrev_b32_e32 v103, 2, v106
	v_lshlrev_b32_e32 v106, 2, v176
	v_add3_u32 v106, s2, v103, v106
	v_max3_f32 v107, v108, v102, s3
	ds_read2_b32 v[206:207], v106 offset0:223 offset1:224
	ds_read2_b32 v[208:209], v106 offset0:225 offset1:226
	ds_read2_b32 v[210:211], v106 offset0:231 offset1:232
	ds_read2_b32 v[212:213], v106 offset0:233 offset1:234
	ds_read2_b32 v[214:215], v106 offset0:239 offset1:240
	ds_read2_b32 v[216:217], v106 offset0:241 offset1:242
	ds_read2_b32 v[218:219], v106 offset0:247 offset1:248
	ds_read2_b32 v[220:221], v106 offset0:249 offset1:250
	s_waitcnt lgkmcnt(8)
	s_waitcnt lgkmcnt(7)
	v_add_f32_e32 v103, v80, v206
	v_add_f32_e32 v80, v81, v207
	v_max3_f32 v107, v107, v103, v80
	s_waitcnt lgkmcnt(6)
	v_add_f32_e32 v82, v82, v208
	v_add_f32_e32 v81, v83, v209
	v_max3_f32 v107, v107, v82, v81
	s_waitcnt lgkmcnt(5)
	v_add_f32_e32 v84, v84, v210
	v_add_f32_e32 v83, v85, v211
	v_max3_f32 v107, v107, v84, v83
	s_waitcnt lgkmcnt(4)
	v_add_f32_e32 v86, v86, v212
	v_add_f32_e32 v85, v87, v213
	v_max3_f32 v107, v107, v86, v85
	s_waitcnt lgkmcnt(3)
	v_add_f32_e32 v88, v88, v214
	v_add_f32_e32 v87, v89, v215
	v_max3_f32 v107, v107, v88, v87
	s_waitcnt lgkmcnt(2)
	v_add_f32_e32 v90, v90, v216
	v_add_f32_e32 v89, v91, v217
	v_max3_f32 v107, v107, v90, v89
	s_waitcnt lgkmcnt(1)
	v_add_f32_e32 v92, v92, v218
	v_add_f32_e32 v91, v93, v219
	v_max3_f32 v107, v107, v92, v91
	s_waitcnt lgkmcnt(0)
	v_add_f32_e32 v93, v95, v221
	v_add_u32_e32 v206, 0x3fc, v106
	ds_read2_b32 v[210:211], v206 offset1:1
	v_add_u32_e32 v207, 0x404, v106
	ds_read2_b32 v[212:213], v207 offset1:1
	v_add_u32_e32 v208, 0x41c, v106
	ds_read2_b32 v[214:215], v208 offset1:1
	v_add_u32_e32 v209, 0x424, v106
	ds_read2_b32 v[216:217], v209 offset1:1
	v_add_u32_e32 v206, 0x43c, v106
	ds_read2_b32 v[218:219], v206 offset1:1
	v_add_u32_e32 v207, 0x444, v106
	ds_read2_b32 v[222:223], v207 offset1:1
	v_add_u32_e32 v208, 0x45c, v106
	ds_read2_b32 v[224:225], v208 offset1:1
	v_add_u32_e32 v209, 0x464, v106
	ds_read2_b32 v[226:227], v209 offset1:1
	v_add_f32_e32 v94, v94, v220
	v_max3_f32 v107, v107, v94, v93
	s_waitcnt lgkmcnt(7)
	v_add_f32_e32 v95, v64, v210
	v_add_f32_e32 v64, v65, v211
	v_max3_f32 v107, v107, v95, v64
	s_waitcnt lgkmcnt(6)
	v_add_f32_e32 v65, v67, v213
	v_add_f32_e32 v66, v66, v212
	v_max3_f32 v107, v107, v66, v65
	s_waitcnt lgkmcnt(5)
	v_add_f32_e32 v68, v68, v214
	v_add_f32_e32 v67, v69, v215
	v_max3_f32 v69, v107, v68, v67
	s_waitcnt lgkmcnt(4)
	v_add_f32_e32 v107, v70, v216
	v_add_f32_e32 v70, v71, v217
	v_max3_f32 v110, v69, v107, v70
	s_waitcnt lgkmcnt(3)
	v_add_f32_e32 v71, v72, v218
	v_add_f32_e32 v69, v73, v219
	v_max3_f32 v110, v110, v71, v69
	s_waitcnt lgkmcnt(2)
	v_add_f32_e32 v73, v74, v222
	v_add_f32_e32 v72, v75, v223
	v_max3_f32 v110, v110, v73, v72
	s_waitcnt lgkmcnt(1)
	v_add_f32_e32 v75, v76, v224
	v_add_f32_e32 v74, v77, v225
	v_max3_f32 v110, v110, v75, v74
	s_waitcnt lgkmcnt(0)
	v_add_f32_e32 v77, v78, v226
	v_add_f32_e32 v76, v79, v227
	v_cndmask_b32_e64 v79, 0, 1, s[4:5]
	v_max3_f32 v78, v110, v77, v76
	v_cmp_ne_u32_e64 s[2:3], 1, v79
	s_cbranch_vccnz .LBB0_1387
	v_add_u32_e32 v206, 0x47c, v106
	ds_read2_b32 v[210:211], v206 offset1:1
	v_add_u32_e32 v207, 0x484, v106
	ds_read2_b32 v[212:213], v207 offset1:1
	v_add_u32_e32 v208, 0x49c, v106
	ds_read2_b32 v[214:215], v208 offset1:1
	v_add_u32_e32 v209, 0x4a4, v106
	ds_read2_b32 v[216:217], v209 offset1:1
	v_add_u32_e32 v206, 0x4bc, v106
	ds_read2_b32 v[218:219], v206 offset1:1
	v_add_u32_e32 v207, 0x4c4, v106
	ds_read2_b32 v[220:221], v207 offset1:1
	v_add_u32_e32 v208, 0x4dc, v106
	ds_read2_b32 v[222:223], v208 offset1:1
	v_add_u32_e32 v209, 0x4e4, v106
	ds_read2_b32 v[224:225], v209 offset1:1
	s_waitcnt lgkmcnt(8)
	s_waitcnt lgkmcnt(7)
	v_pk_add_f32 v[48:49], v[48:49], v[210:211]
	s_nop 0
	v_max3_f32 v108, v78, v48, v49
	s_waitcnt lgkmcnt(6)
	v_pk_add_f32 v[50:51], v[50:51], v[212:213]
	v_max3_f32 v108, v108, v50, v51
	s_waitcnt lgkmcnt(5)
	v_pk_add_f32 v[52:53], v[52:53], v[214:215]
	v_max3_f32 v108, v108, v52, v53
	s_waitcnt lgkmcnt(4)
	v_pk_add_f32 v[54:55], v[54:55], v[216:217]
	v_max3_f32 v108, v108, v54, v55
	s_waitcnt lgkmcnt(3)
	v_pk_add_f32 v[56:57], v[56:57], v[218:219]
	v_max3_f32 v108, v108, v56, v57
	s_waitcnt lgkmcnt(2)
	v_pk_add_f32 v[58:59], v[58:59], v[220:221]
	v_max3_f32 v108, v108, v58, v59
	s_waitcnt lgkmcnt(1)
	v_pk_add_f32 v[60:61], v[60:61], v[222:223]
	v_max3_f32 v108, v108, v60, v61
	s_waitcnt lgkmcnt(0)
	v_pk_add_f32 v[62:63], v[62:63], v[224:225]
	s_nop 0
	v_max3_f32 v78, v108, v62, v63
.LBB0_1387:
	v_cndmask_b32_e64 v79, 0, 1, s[6:7]
	v_cmp_ne_u32_e64 s[4:5], 1, v79
	s_andn2_b64 vcc, exec, s[6:7]
	s_mov_b32 s63, 0x8400
	s_mov_b64 s[56:57], 0x1a8a9500
	s_mov_b64 s[58:59], s[12:13]
	s_cbranch_vccnz .LBB0_1395
	v_add_u32_e32 v206, 0x4fc, v106
	ds_read2_b32 v[210:211], v206 offset1:1
	v_add_u32_e32 v207, 0x504, v106
	ds_read2_b32 v[212:213], v207 offset1:1
	v_add_u32_e32 v208, 0x51c, v106
	ds_read2_b32 v[214:215], v208 offset1:1
	v_add_u32_e32 v209, 0x524, v106
	ds_read2_b32 v[216:217], v209 offset1:1
	v_add_u32_e32 v206, 0x53c, v106
	ds_read2_b32 v[218:219], v206 offset1:1
	v_add_u32_e32 v207, 0x544, v106
	ds_read2_b32 v[220:221], v207 offset1:1
	v_add_u32_e32 v208, 0x55c, v106
	ds_read2_b32 v[222:223], v208 offset1:1
	v_add_u32_e32 v209, 0x564, v106
	ds_read2_b32 v[224:225], v209 offset1:1
	s_waitcnt lgkmcnt(8)
	s_waitcnt lgkmcnt(7)
	v_pk_add_f32 v[32:33], v[32:33], v[210:211]
	s_nop 0
	v_max3_f32 v108, v78, v32, v33
	s_waitcnt lgkmcnt(6)
	v_pk_add_f32 v[34:35], v[34:35], v[212:213]
	v_max3_f32 v108, v108, v34, v35
	s_waitcnt lgkmcnt(5)
	v_pk_add_f32 v[36:37], v[36:37], v[214:215]
	v_max3_f32 v108, v108, v36, v37
	s_waitcnt lgkmcnt(4)
	v_pk_add_f32 v[38:39], v[38:39], v[216:217]
	v_max3_f32 v108, v108, v38, v39
	s_waitcnt lgkmcnt(3)
	v_pk_add_f32 v[40:41], v[40:41], v[218:219]
	v_max3_f32 v108, v108, v40, v41
	s_waitcnt lgkmcnt(2)
	v_pk_add_f32 v[42:43], v[42:43], v[220:221]
	v_max3_f32 v108, v108, v42, v43
	s_waitcnt lgkmcnt(1)
	v_pk_add_f32 v[44:45], v[44:45], v[222:223]
	v_max3_f32 v108, v108, v44, v45
	s_waitcnt lgkmcnt(0)
	v_pk_add_f32 v[46:47], v[46:47], v[224:225]
	s_nop 0
	v_max3_f32 v78, v108, v46, v47
	v_cndmask_b32_e64 v79, 0, 1, s[8:9]
	v_cmp_ne_u32_e64 s[6:7], 1, v79
	s_andn2_b64 vcc, exec, s[8:9]
	s_cbranch_vccz .LBB0_1396

.LBB0_1390:
	v_add_u32_e32 v206, 0x5fc, v106
	ds_read2_b32 v[210:211], v206 offset1:1
	v_add_u32_e32 v207, 0x604, v106
	ds_read2_b32 v[212:213], v207 offset1:1
	v_add_u32_e32 v208, 0x61c, v106
	ds_read2_b32 v[214:215], v208 offset1:1
	v_add_u32_e32 v209, 0x624, v106
	ds_read2_b32 v[216:217], v209 offset1:1
	v_add_u32_e32 v206, 0x63c, v106
	ds_read2_b32 v[218:219], v206 offset1:1
	v_add_u32_e32 v207, 0x644, v106
	ds_read2_b32 v[220:221], v207 offset1:1
	v_add_u32_e32 v208, 0x65c, v106
	ds_read2_b32 v[222:223], v208 offset1:1
	v_add_u32_e32 v209, 0x664, v106
	ds_read2_b32 v[224:225], v209 offset1:1
	s_waitcnt lgkmcnt(8)
	s_waitcnt lgkmcnt(7)
	v_pk_add_f32 v[0:1], v[0:1], v[210:211]
	s_nop 0
	v_max3_f32 v108, v78, v0, v1
	s_waitcnt lgkmcnt(6)
	v_pk_add_f32 v[2:3], v[2:3], v[212:213]
	v_max3_f32 v108, v108, v2, v3
	s_waitcnt lgkmcnt(5)
	v_pk_add_f32 v[4:5], v[4:5], v[214:215]
	v_max3_f32 v108, v108, v4, v5
	s_waitcnt lgkmcnt(4)
	v_pk_add_f32 v[6:7], v[6:7], v[216:217]
	v_max3_f32 v108, v108, v6, v7
	s_waitcnt lgkmcnt(3)
	v_pk_add_f32 v[8:9], v[8:9], v[218:219]
	v_max3_f32 v108, v108, v8, v9
	s_waitcnt lgkmcnt(2)
	v_pk_add_f32 v[10:11], v[10:11], v[220:221]
	v_max3_f32 v108, v108, v10, v11
	s_waitcnt lgkmcnt(1)
	v_pk_add_f32 v[12:13], v[12:13], v[222:223]
	v_max3_f32 v108, v108, v12, v13
	s_waitcnt lgkmcnt(0)
	v_pk_add_f32 v[14:15], v[14:15], v[224:225]
	s_nop 0
	v_max3_f32 v78, v108, v14, v15

.LBB0_1396:
	v_add_u32_e32 v206, 0x57c, v106
	ds_read2_b32 v[210:211], v206 offset1:1
	v_add_u32_e32 v207, 0x584, v106
	ds_read2_b32 v[212:213], v207 offset1:1
	v_add_u32_e32 v208, 0x59c, v106
	ds_read2_b32 v[214:215], v208 offset1:1
	v_add_u32_e32 v209, 0x5a4, v106
	ds_read2_b32 v[216:217], v209 offset1:1
	v_add_u32_e32 v206, 0x5bc, v106
	ds_read2_b32 v[218:219], v206 offset1:1
	v_add_u32_e32 v207, 0x5c4, v106
	ds_read2_b32 v[220:221], v207 offset1:1
	v_add_u32_e32 v208, 0x5dc, v106
	ds_read2_b32 v[222:223], v208 offset1:1
	v_add_u32_e32 v209, 0x5e4, v106
	ds_read2_b32 v[224:225], v209 offset1:1
	s_waitcnt lgkmcnt(8)
	s_waitcnt lgkmcnt(7)
	v_pk_add_f32 v[16:17], v[16:17], v[210:211]
	s_nop 0
	v_max3_f32 v108, v78, v16, v17
	s_waitcnt lgkmcnt(6)
	v_pk_add_f32 v[18:19], v[18:19], v[212:213]
	v_max3_f32 v108, v108, v18, v19
	s_waitcnt lgkmcnt(5)
	v_pk_add_f32 v[20:21], v[20:21], v[214:215]
	v_max3_f32 v108, v108, v20, v21
	s_waitcnt lgkmcnt(4)
	v_pk_add_f32 v[22:23], v[22:23], v[216:217]
	v_max3_f32 v108, v108, v22, v23
	s_waitcnt lgkmcnt(3)
	v_pk_add_f32 v[24:25], v[24:25], v[218:219]
	v_max3_f32 v108, v108, v24, v25
	s_waitcnt lgkmcnt(2)
	v_pk_add_f32 v[26:27], v[26:27], v[220:221]
	v_max3_f32 v108, v108, v26, v27
	s_waitcnt lgkmcnt(1)
	v_pk_add_f32 v[28:29], v[28:29], v[222:223]
	v_max3_f32 v108, v108, v28, v29
	s_waitcnt lgkmcnt(0)
	v_pk_add_f32 v[30:31], v[30:31], v[224:225]
	s_nop 0
	v_max3_f32 v78, v108, v30, v31
	v_cndmask_b32_e64 v79, 0, 1, s[96:97]
	v_cmp_ne_u32_e64 s[8:9], 1, v79
	s_andn2_b64 vcc, exec, s[96:97]
	s_cbranch_vccz .LBB0_1390
	s_branch .LBB0_1391

.LBB0_1401:
	ds_bpermute_b32 v65, v175, v64
	v_sub_f32_e32 v66, v104, v106
	v_exp_f32_e32 v66, v66
	s_waitcnt lgkmcnt(0)
	v_add_f32_e32 v64, v64, v65
	v_add_f32_e32 v64, v66, v64
	v_div_scale_f32 v65, s[12:13], v64, v64, 1.0
	v_rcp_f32_e32 v66, v65
	v_div_scale_f32 v67, vcc, 1.0, v64, 1.0
	v_fma_f32 v68, -v65, v66, 1.0
	v_fmac_f32_e32 v66, v68, v66
	v_mul_f32_e32 v68, v67, v66
	v_fma_f32 v69, -v65, v68, v67
	v_fmac_f32_e32 v68, v69, v66
	v_fma_f32 v65, -v65, v68, v67
	v_div_fmas_f32 v65, v65, v66, v68
	v_div_fixup_f32 v104, v65, v64, 1.0
	v_mul_f32_e32 v64, v96, v104
	v_mul_f32_e32 v65, v97, v104
	v_cvt_pk_bf16_f32 v80, v64, v65
	v_mul_f32_e32 v64, v78, v104
	v_mul_f32_e32 v65, v79, v104
	v_cvt_pk_bf16_f32 v81, v64, v65
	v_mul_f32_e32 v64, v98, v104
	v_mul_f32_e32 v65, v99, v104
	v_cvt_pk_bf16_f32 v82, v64, v65
	v_mul_f32_e32 v64, v100, v104
	v_mul_f32_e32 v65, v101, v104
	v_cvt_pk_bf16_f32 v83, v64, v65
	ds_read_b128 v[206:209], v197 offset:45568
	ds_read_b128 v[210:213], v197 offset:46592
	ds_read_b128 v[214:217], v197 offset:49664
	ds_read_b128 v[218:221], v197 offset:50688
	ds_read_b128 v[222:225], v197 offset:51712
	ds_read_b128 v[226:229], v197 offset:52736
	ds_read_b128 v[230:233], v197 offset:53760
	ds_read_b128 v[234:237], v197 offset:54784
	v_mul_f32_e32 v96, v102, v104
	v_mul_f32_e32 v97, v105, v104
	s_waitcnt lgkmcnt(8)
	s_waitcnt lgkmcnt(7)
	v_mfma_f32_32x32x16_bf16 v[64:79], v[80:83], v[206:209], 0
	v_cvt_pk_bf16_f32 v96, v96, v97
	v_mul_f32_e32 v97, v108, v104
	v_mul_f32_e32 v98, v110, v104
	v_cvt_pk_bf16_f32 v97, v97, v98
	v_mul_f32_e32 v98, v130, v104
	v_mul_f32_e32 v99, v136, v104
	v_cvt_pk_bf16_f32 v98, v98, v99
	v_mul_f32_e32 v99, v139, v104
	v_mul_f32_e32 v100, v142, v104
	v_cvt_pk_bf16_f32 v99, v99, v100
	s_waitcnt lgkmcnt(6)
	v_mfma_f32_32x32x16_bf16 v[80:95], v[80:83], v[210:213], 0
	v_mul_f32_e32 v100, v199, v104
	s_and_b64 vcc, exec, s[2:3]
	s_waitcnt lgkmcnt(5)
	v_mfma_f32_32x32x16_bf16 v[64:79], v[96:99], v[214:217], v[64:79]
	s_waitcnt lgkmcnt(4)
	v_mfma_f32_32x32x16_bf16 v[80:95], v[96:99], v[218:221], v[80:95]
	v_mul_f32_e32 v96, v103, v104
	v_mul_f32_e32 v97, v111, v104
	v_cvt_pk_bf16_f32 v96, v96, v97
	v_mul_f32_e32 v97, v131, v104
	v_mul_f32_e32 v98, v132, v104
	v_cvt_pk_bf16_f32 v97, v97, v98
	v_mul_f32_e32 v98, v134, v104
	v_mul_f32_e32 v99, v143, v104
	v_cvt_pk_bf16_f32 v98, v98, v99
	v_mul_f32_e32 v99, v145, v104
	v_cvt_pk_bf16_f32 v99, v99, v100
	s_waitcnt lgkmcnt(3)
	v_mfma_f32_32x32x16_bf16 v[64:79], v[96:99], v[222:225], v[64:79]
	s_waitcnt lgkmcnt(2)
	v_mfma_f32_32x32x16_bf16 v[80:95], v[96:99], v[226:229], v[80:95]
	v_mul_f32_e32 v96, v109, v104
	v_mul_f32_e32 v97, v133, v104
	v_cvt_pk_bf16_f32 v96, v96, v97
	v_mul_f32_e32 v97, v135, v104
	v_mul_f32_e32 v98, v137, v104
	v_cvt_pk_bf16_f32 v97, v97, v98
	v_mul_f32_e32 v98, v140, v104
	v_mul_f32_e32 v99, v200, v104
	v_cvt_pk_bf16_f32 v98, v98, v99
	v_mul_f32_e32 v99, v201, v104
	v_mul_f32_e32 v100, v202, v104
	v_cvt_pk_bf16_f32 v99, v99, v100
	s_waitcnt lgkmcnt(1)
	v_mfma_f32_32x32x16_bf16 v[64:79], v[96:99], v[230:233], v[64:79]
	s_waitcnt lgkmcnt(0)
	v_mfma_f32_32x32x16_bf16 v[80:95], v[96:99], v[234:237], v[80:95]
	v_mul_f32_e32 v96, v107, v104
	v_mul_f32_e32 v97, v138, v104
	v_cvt_pk_bf16_f32 v96, v96, v97
	v_mul_f32_e32 v97, v141, v104
	v_mul_f32_e32 v98, v144, v104
	v_cvt_pk_bf16_f32 v97, v97, v98
	v_mul_f32_e32 v98, v198, v104
	v_mul_f32_e32 v99, v203, v104
	v_cvt_pk_bf16_f32 v98, v98, v99
	v_mul_f32_e32 v99, v204, v104
	v_mul_f32_e32 v100, v205, v104
	v_cvt_pk_bf16_f32 v99, v99, v100
	ds_read_b128 v[206:209], v197 offset:55808
	ds_read_b128 v[210:213], v197 offset:56832
	s_waitcnt lgkmcnt(2)
	s_waitcnt lgkmcnt(1)
	v_mfma_f32_32x32x16_bf16 v[64:79], v[96:99], v[206:209], v[64:79]
	s_waitcnt lgkmcnt(0)
	v_mfma_f32_32x32x16_bf16 v[80:95], v[96:99], v[210:213], v[80:95]
	v_mov_b32_e32 v102, v212
	v_mov_b32_e32 v103, v213
	v_mov_b32_e32 v148, v218
	v_mov_b32_e32 v149, v219
	v_mov_b32_e32 v150, v220
	v_mov_b32_e32 v151, v221
	s_nop 1
	s_cbranch_vccnz .LBB0_1405
	v_mul_f32_e32 v96, v48, v104
	v_mul_f32_e32 v97, v49, v104
	v_cvt_pk_bf16_f32 v96, v96, v97
	v_mul_f32_e32 v97, v50, v104
	v_mul_f32_e32 v98, v51, v104
	v_cvt_pk_bf16_f32 v97, v97, v98
	v_mul_f32_e32 v98, v52, v104
	v_mul_f32_e32 v99, v53, v104
	v_cvt_pk_bf16_f32 v98, v98, v99
	v_mul_f32_e32 v99, v54, v104
	v_mul_f32_e32 v100, v55, v104
	v_cvt_pk_bf16_f32 v99, v99, v100
	ds_read_b128 v[206:209], v197 offset:57856
	ds_read_b128 v[210:213], v197 offset:58880
	ds_read_b128 v[214:217], v197 offset:59904
	ds_read_b128 v[218:221], v197 offset:60928
	s_waitcnt lgkmcnt(4)
	s_waitcnt lgkmcnt(3)
	v_mfma_f32_32x32x16_bf16 v[64:79], v[96:99], v[206:209], v[64:79]
	s_waitcnt lgkmcnt(2)
	v_mfma_f32_32x32x16_bf16 v[80:95], v[96:99], v[210:213], v[80:95]
	v_mul_f32_e32 v96, v56, v104
	v_mul_f32_e32 v97, v57, v104
	v_cvt_pk_bf16_f32 v96, v96, v97
	v_mul_f32_e32 v97, v58, v104
	v_mul_f32_e32 v98, v59, v104
	v_cvt_pk_bf16_f32 v97, v97, v98
	v_mul_f32_e32 v98, v60, v104
	v_mul_f32_e32 v99, v61, v104
	v_cvt_pk_bf16_f32 v98, v98, v99
	v_mul_f32_e32 v99, v62, v104
	v_mul_f32_e32 v100, v63, v104
	v_cvt_pk_bf16_f32 v99, v99, v100
	s_waitcnt lgkmcnt(1)
	v_mfma_f32_32x32x16_bf16 v[64:79], v[96:99], v[214:217], v[64:79]
	s_waitcnt lgkmcnt(0)
	v_mfma_f32_32x32x16_bf16 v[80:95], v[96:99], v[218:221], v[80:95]
	s_and_b64 vcc, exec, s[4:5]
	v_mov_b32_e32 v102, v220
	v_mov_b32_e32 v103, v221
	s_nop 1
	s_cbranch_vccz .LBB0_1406

.LBB0_1404:
	v_mul_f32_e32 v97, v16, v104
	v_mul_f32_e32 v98, v17, v104
	v_cvt_pk_bf16_f32 v98, v97, v98
	v_mul_f32_e32 v97, v18, v104
	v_mul_f32_e32 v99, v19, v104
	v_cvt_pk_bf16_f32 v99, v97, v99
	v_mul_f32_e32 v97, v20, v104
	v_mul_f32_e32 v100, v21, v104
	v_mul_f32_e32 v101, v23, v104
	v_cvt_pk_bf16_f32 v100, v97, v100
	v_mul_f32_e32 v97, v22, v104
	v_cvt_pk_bf16_f32 v101, v97, v101
	ds_read_b128 v[206:209], v96 offset:49152
	ds_read_b128 v[210:213], v96 offset:50176
	ds_read_b128 v[214:217], v96 offset:51200
	ds_read_b128 v[218:221], v96 offset:52224
	s_waitcnt lgkmcnt(4)
	s_waitcnt lgkmcnt(3)
	v_mfma_f32_32x32x16_bf16 v[64:79], v[98:101], v[206:209], v[64:79]
	v_mul_f32_e32 v97, v24, v104
	s_waitcnt lgkmcnt(2)
	v_mfma_f32_32x32x16_bf16 v[80:95], v[98:101], v[210:213], v[80:95]
	v_mul_f32_e32 v98, v25, v104
	v_cvt_pk_bf16_f32 v98, v97, v98
	v_mul_f32_e32 v97, v26, v104
	v_mul_f32_e32 v99, v27, v104
	v_cvt_pk_bf16_f32 v99, v97, v99
	v_mul_f32_e32 v97, v28, v104
	v_mul_f32_e32 v100, v29, v104
	v_mul_f32_e32 v101, v31, v104
	v_cvt_pk_bf16_f32 v100, v97, v100
	v_mul_f32_e32 v97, v30, v104
	v_cvt_pk_bf16_f32 v101, v97, v101
	s_waitcnt lgkmcnt(1)
	v_mfma_f32_32x32x16_bf16 v[64:79], v[98:101], v[214:217], v[64:79]
	s_waitcnt lgkmcnt(0)
	v_mfma_f32_32x32x16_bf16 v[80:95], v[98:101], v[218:221], v[80:95]
	s_and_b64 vcc, exec, s[8:9]
	v_mov_b32_e32 v106, v218
	v_mov_b32_e32 v107, v219
	v_mov_b32_e32 v108, v220
	v_mov_b32_e32 v109, v221
	s_nop 1
	s_cbranch_vccnz .LBB0_1319
	s_branch .LBB0_1408

.LBB0_1406:
	v_mul_f32_e32 v96, v32, v104
	v_mul_f32_e32 v97, v33, v104
	v_cvt_pk_bf16_f32 v96, v96, v97
	v_mul_f32_e32 v97, v34, v104
	v_mul_f32_e32 v98, v35, v104
	v_cvt_pk_bf16_f32 v97, v97, v98
	v_mul_f32_e32 v98, v36, v104
	v_mul_f32_e32 v99, v37, v104
	v_cvt_pk_bf16_f32 v98, v98, v99
	v_mul_f32_e32 v99, v38, v104
	v_mul_f32_e32 v100, v39, v104
	v_cvt_pk_bf16_f32 v99, v99, v100
	ds_read_b128 v[206:209], v197 offset:61952
	ds_read_b128 v[210:213], v197 offset:62976
	ds_read_b128 v[214:217], v197 offset:64000
	ds_read_b128 v[218:221], v197 offset:65024
	s_waitcnt lgkmcnt(4)
	s_waitcnt lgkmcnt(3)
	v_mfma_f32_32x32x16_bf16 v[64:79], v[96:99], v[206:209], v[64:79]
	s_waitcnt lgkmcnt(2)
	v_mfma_f32_32x32x16_bf16 v[80:95], v[96:99], v[210:213], v[80:95]
	v_mul_f32_e32 v96, v40, v104
	v_mul_f32_e32 v97, v41, v104
	v_cvt_pk_bf16_f32 v96, v96, v97
	v_mul_f32_e32 v97, v42, v104
	v_mul_f32_e32 v98, v43, v104
	v_cvt_pk_bf16_f32 v97, v97, v98
	v_mul_f32_e32 v98, v44, v104
	v_mul_f32_e32 v99, v45, v104
	v_cvt_pk_bf16_f32 v98, v98, v99
	v_mul_f32_e32 v99, v46, v104
	v_mul_f32_e32 v100, v47, v104
	v_cvt_pk_bf16_f32 v99, v99, v100
	s_waitcnt lgkmcnt(1)
	v_mfma_f32_32x32x16_bf16 v[64:79], v[96:99], v[214:217], v[64:79]
	s_waitcnt lgkmcnt(0)
	v_mfma_f32_32x32x16_bf16 v[80:95], v[96:99], v[218:221], v[80:95]
	s_and_b64 vcc, exec, s[6:7]
	v_add_u32_e32 v96, 0x4200, v197
	v_mov_b32_e32 v102, v220
	v_mov_b32_e32 v103, v221
	s_nop 1
	s_cbranch_vccz .LBB0_1404

.LBB0_1408:
	v_mul_f32_e32 v97, v0, v104
	v_mul_f32_e32 v98, v1, v104
	v_cvt_pk_bf16_f32 v98, v97, v98
	v_mul_f32_e32 v97, v2, v104
	v_mul_f32_e32 v99, v3, v104
	v_cvt_pk_bf16_f32 v99, v97, v99
	v_mul_f32_e32 v97, v4, v104
	v_mul_f32_e32 v100, v5, v104
	v_mul_f32_e32 v101, v7, v104
	v_cvt_pk_bf16_f32 v100, v97, v100
	v_mul_f32_e32 v97, v6, v104
	v_cvt_pk_bf16_f32 v101, v97, v101
	ds_read_b128 v[206:209], v96 offset:53248
	ds_read_b128 v[210:213], v96 offset:54272
	ds_read_b128 v[214:217], v96 offset:55296
	ds_read_b128 v[218:221], v96 offset:56320
	s_waitcnt lgkmcnt(4)
	s_waitcnt lgkmcnt(3)
	v_mfma_f32_32x32x16_bf16 v[64:79], v[98:101], v[206:209], v[64:79]
	v_mul_f32_e32 v97, v8, v104
	s_waitcnt lgkmcnt(2)
	v_mfma_f32_32x32x16_bf16 v[80:95], v[98:101], v[210:213], v[80:95]
	v_mul_f32_e32 v98, v9, v104
	v_cvt_pk_bf16_f32 v98, v97, v98
	v_mul_f32_e32 v97, v10, v104
	v_mul_f32_e32 v99, v11, v104
	v_cvt_pk_bf16_f32 v99, v97, v99
	v_mul_f32_e32 v97, v12, v104
	v_mul_f32_e32 v100, v13, v104
	v_mul_f32_e32 v101, v15, v104
	v_cvt_pk_bf16_f32 v100, v97, v100
	v_mul_f32_e32 v97, v14, v104
	v_cvt_pk_bf16_f32 v101, v97, v101
	s_waitcnt lgkmcnt(1)
	v_mfma_f32_32x32x16_bf16 v[64:79], v[98:101], v[214:217], v[64:79]
	s_waitcnt lgkmcnt(0)
	v_mfma_f32_32x32x16_bf16 v[80:95], v[98:101], v[218:221], v[80:95]
	v_mov_b32_e32 v102, v218
	v_mov_b32_e32 v103, v219
	v_mov_b32_e32 v104, v220
	v_mov_b32_e32 v105, v221
	v_mov_b32_e32 v106, v210
	v_mov_b32_e32 v107, v211
	v_mov_b32_e32 v108, v212
	v_mov_b32_e32 v109, v213
	s_nop 1
	s_branch .LBB0_1319
